# neighbourhood-attention steps: mask-apply wait relaxed from vmcnt(0) to the closing-barrier count (K/V DMAs stay in flight)
# baseline (speedup 1.0000x reference)
; __device__ __forceinline__ void na_apply(f32x16&p0,f32x16&p1,const u32x4_t*mf,bool ok){
;   if(!ok){ const float NEG=-INFINITY;
;     #pragma unroll
;     for(int rr=0;rr<16;++rr){p0[rr]=NEG;p1[rr]=NEG;}
;     return; }
;   #pragma unroll
;   for(int rr=0;rr<16;++rr){ const unsigned w0=mf[rr>>3][(rr>>1)&3], w1=mf[2+(rr>>3)][(rr>>1)&3];
;     p0[rr]+=__builtin_bit_cast(float,(rr&1)?(w0&0xffff0000u):(w0<<16)); p1[rr]+=__builtin_bit_cast(float,(rr&1)?(w1&0xffff0000u):(w1<<16)); }
; }
.LBB0_339:
	s_andn2_b64 vcc, exec, s[64:65]
	s_cbranch_vccnz .LBB0_341
	s_waitcnt vmcnt(2)
	v_lshlrev_b32_e32 v50, 16, v158
	v_and_b32_e32 v51, 0xffff0000, v158
	v_add_f32_e32 v66, v66, v50
	v_add_f32_e32 v67, v67, v51
	v_lshlrev_b32_e32 v50, 16, v154
	v_and_b32_e32 v51, 0xffff0000, v154
	v_lshlrev_b32_e32 v52, 16, v159
	v_and_b32_e32 v53, 0xffff0000, v159
	v_lshlrev_b32_e32 v54, 16, v160
	v_and_b32_e32 v55, 0xffff0000, v160
	v_lshlrev_b32_e32 v56, 16, v161
	v_and_b32_e32 v57, 0xffff0000, v161
	v_lshlrev_b32_e32 v58, 16, v150
	v_and_b32_e32 v59, 0xffff0000, v150
	v_lshlrev_b32_e32 v60, 16, v151
	v_and_b32_e32 v61, 0xffff0000, v151
	v_lshlrev_b32_e32 v62, 16, v152
	v_and_b32_e32 v63, 0xffff0000, v152
	v_add_f32_e32 v50, v98, v50
	v_add_f32_e32 v51, v99, v51
	v_add_f32_e32 v68, v68, v52
	v_add_f32_e32 v69, v69, v53
	v_lshlrev_b32_e32 v52, 16, v155
	v_and_b32_e32 v53, 0xffff0000, v155
	v_add_f32_e32 v70, v70, v54
	v_add_f32_e32 v71, v71, v55
	v_lshlrev_b32_e32 v54, 16, v156
	v_and_b32_e32 v55, 0xffff0000, v156
	v_add_f32_e32 v72, v72, v56
	v_add_f32_e32 v73, v73, v57
	v_lshlrev_b32_e32 v56, 16, v157
	v_and_b32_e32 v57, 0xffff0000, v157
	v_add_f32_e32 v74, v74, v58
	v_add_f32_e32 v75, v75, v59
	v_lshlrev_b32_e32 v58, 16, v146
	v_and_b32_e32 v59, 0xffff0000, v146
	v_add_f32_e32 v76, v76, v60
	v_add_f32_e32 v77, v77, v61
	v_lshlrev_b32_e32 v60, 16, v147
	v_and_b32_e32 v61, 0xffff0000, v147
	v_add_f32_e32 v78, v78, v62
	v_add_f32_e32 v79, v79, v63
	v_lshlrev_b32_e32 v62, 16, v148
	v_and_b32_e32 v63, 0xffff0000, v148
	v_lshlrev_b32_e32 v64, 16, v149
	v_lshlrev_b32_e32 v98, 16, v153
	v_and_b32_e32 v99, 0xffff0000, v153
	v_and_b32_e32 v65, 0xffff0000, v149
	v_add_f32_e32 v52, v100, v52
	v_add_f32_e32 v53, v101, v53
	v_add_f32_e32 v54, v102, v54
	v_add_f32_e32 v55, v103, v55
	v_add_f32_e32 v56, v104, v56
	v_add_f32_e32 v57, v105, v57
	v_add_f32_e32 v58, v106, v58
	v_add_f32_e32 v59, v107, v59
	v_add_f32_e32 v60, v108, v60
	v_add_f32_e32 v61, v109, v61
	v_add_f32_e32 v62, v110, v62
	v_add_f32_e32 v63, v111, v63
	v_add_f32_e32 v64, v112, v64
	v_add_f32_e32 v80, v80, v98
	v_add_f32_e32 v81, v81, v99
	v_add_f32_e32 v65, v113, v65
	s_branch .LBB0_342

; __device__ __forceinline__ void na_apply(f32x16&p0,f32x16&p1,const u32x4_t*mf,bool ok){
;   if(!ok){ const float NEG=-INFINITY;
;     #pragma unroll
;     for(int rr=0;rr<16;++rr){p0[rr]=NEG;p1[rr]=NEG;}
;     return; }
;   #pragma unroll
;   for(int rr=0;rr<16;++rr){ const unsigned w0=mf[rr>>3][(rr>>1)&3], w1=mf[2+(rr>>3)][(rr>>1)&3];
;     p0[rr]+=__builtin_bit_cast(float,(rr&1)?(w0&0xffff0000u):(w0<<16)); p1[rr]+=__builtin_bit_cast(float,(rr&1)?(w1&0xffff0000u):(w1<<16)); }
; }
.LBB0_350:
	s_andn2_b64 vcc, exec, s[66:67]
	s_cbranch_vccnz .LBB0_352
	s_waitcnt vmcnt(2)
	v_lshlrev_b32_e32 v50, 16, v158
	v_and_b32_e32 v51, 0xffff0000, v158
	v_lshlrev_b32_e32 v52, 16, v159
	v_and_b32_e32 v53, 0xffff0000, v159
	v_lshlrev_b32_e32 v54, 16, v160
	v_and_b32_e32 v55, 0xffff0000, v160
	v_lshlrev_b32_e32 v56, 16, v161
	v_and_b32_e32 v57, 0xffff0000, v161
	v_lshlrev_b32_e32 v58, 16, v150
	v_and_b32_e32 v59, 0xffff0000, v150
	v_lshlrev_b32_e32 v60, 16, v151
	v_and_b32_e32 v61, 0xffff0000, v151
	v_lshlrev_b32_e32 v62, 16, v152
	v_and_b32_e32 v63, 0xffff0000, v152
	v_add_f32_e32 v66, v82, v50
	v_add_f32_e32 v67, v83, v51
	v_lshlrev_b32_e32 v50, 16, v154
	v_and_b32_e32 v51, 0xffff0000, v154
	v_add_f32_e32 v68, v84, v52
	v_add_f32_e32 v69, v85, v53
	v_lshlrev_b32_e32 v52, 16, v155
	v_and_b32_e32 v53, 0xffff0000, v155
	v_add_f32_e32 v70, v86, v54
	v_add_f32_e32 v71, v87, v55
	v_lshlrev_b32_e32 v54, 16, v156
	v_and_b32_e32 v55, 0xffff0000, v156
	v_add_f32_e32 v72, v88, v56
	v_add_f32_e32 v73, v89, v57
	v_lshlrev_b32_e32 v56, 16, v157
	v_and_b32_e32 v57, 0xffff0000, v157
	v_add_f32_e32 v74, v90, v58
	v_add_f32_e32 v75, v91, v59
	v_lshlrev_b32_e32 v58, 16, v146
	v_and_b32_e32 v59, 0xffff0000, v146
	v_add_f32_e32 v76, v92, v60
	v_add_f32_e32 v77, v93, v61
	v_lshlrev_b32_e32 v60, 16, v147
	v_and_b32_e32 v61, 0xffff0000, v147
	v_add_f32_e32 v78, v94, v62
	v_add_f32_e32 v79, v95, v63
	v_lshlrev_b32_e32 v62, 16, v148
	v_and_b32_e32 v63, 0xffff0000, v148
	v_lshlrev_b32_e32 v64, 16, v149
	v_lshlrev_b32_e32 v80, 16, v153
	v_and_b32_e32 v81, 0xffff0000, v153
	v_and_b32_e32 v65, 0xffff0000, v149
	v_add_f32_e32 v50, v98, v50
	v_add_f32_e32 v51, v99, v51
	v_add_f32_e32 v52, v100, v52
	v_add_f32_e32 v53, v101, v53
	v_add_f32_e32 v54, v102, v54
	v_add_f32_e32 v55, v103, v55
	v_add_f32_e32 v56, v104, v56
	v_add_f32_e32 v57, v105, v57
	v_add_f32_e32 v58, v106, v58
	v_add_f32_e32 v59, v107, v59
	v_add_f32_e32 v60, v108, v60
	v_add_f32_e32 v61, v109, v61
	v_add_f32_e32 v62, v110, v62
	v_add_f32_e32 v63, v111, v63
	v_add_f32_e32 v64, v112, v64
	v_add_f32_e32 v80, v96, v80
	v_add_f32_e32 v81, v97, v81
	v_add_f32_e32 v65, v113, v65
	s_branch .LBB0_353

; __device__ __forceinline__ void na_apply(f32x16&p0,f32x16&p1,const u32x4_t*mf,bool ok){
;   if(!ok){ const float NEG=-INFINITY;
;     #pragma unroll
;     for(int rr=0;rr<16;++rr){p0[rr]=NEG;p1[rr]=NEG;}
;     return; }
;   #pragma unroll
;   for(int rr=0;rr<16;++rr){ const unsigned w0=mf[rr>>3][(rr>>1)&3], w1=mf[2+(rr>>3)][(rr>>1)&3];
;     p0[rr]+=__builtin_bit_cast(float,(rr&1)?(w0&0xffff0000u):(w0<<16)); p1[rr]+=__builtin_bit_cast(float,(rr&1)?(w1&0xffff0000u):(w1<<16)); }
; }
.LBB0_378:
	s_andn2_b64 vcc, exec, s[64:65]
	s_cbranch_vccnz .LBB0_380
	s_waitcnt vmcnt(2)
	v_lshlrev_b32_e32 v50, 16, v158
	v_and_b32_e32 v51, 0xffff0000, v158
	v_lshlrev_b32_e32 v52, 16, v159
	v_and_b32_e32 v53, 0xffff0000, v159
	v_lshlrev_b32_e32 v54, 16, v160
	v_and_b32_e32 v55, 0xffff0000, v160
	v_lshlrev_b32_e32 v56, 16, v161
	v_and_b32_e32 v57, 0xffff0000, v161
	v_lshlrev_b32_e32 v58, 16, v150
	v_and_b32_e32 v59, 0xffff0000, v150
	v_lshlrev_b32_e32 v60, 16, v151
	v_and_b32_e32 v61, 0xffff0000, v151
	v_lshlrev_b32_e32 v62, 16, v152
	v_and_b32_e32 v63, 0xffff0000, v152
	v_add_f32_e32 v66, v82, v50
	v_add_f32_e32 v67, v83, v51
	v_lshlrev_b32_e32 v50, 16, v154
	v_and_b32_e32 v51, 0xffff0000, v154
	v_add_f32_e32 v68, v84, v52
	v_add_f32_e32 v69, v85, v53
	v_lshlrev_b32_e32 v52, 16, v155
	v_and_b32_e32 v53, 0xffff0000, v155
	v_add_f32_e32 v70, v86, v54
	v_add_f32_e32 v71, v87, v55
	v_lshlrev_b32_e32 v54, 16, v156
	v_and_b32_e32 v55, 0xffff0000, v156
	v_add_f32_e32 v72, v88, v56
	v_add_f32_e32 v73, v89, v57
	v_lshlrev_b32_e32 v56, 16, v157
	v_and_b32_e32 v57, 0xffff0000, v157
	v_add_f32_e32 v74, v90, v58
	v_add_f32_e32 v75, v91, v59
	v_lshlrev_b32_e32 v58, 16, v146
	v_and_b32_e32 v59, 0xffff0000, v146
	v_add_f32_e32 v76, v92, v60
	v_add_f32_e32 v77, v93, v61
	v_lshlrev_b32_e32 v60, 16, v147
	v_and_b32_e32 v61, 0xffff0000, v147
	v_add_f32_e32 v78, v94, v62
	v_add_f32_e32 v79, v95, v63
	v_lshlrev_b32_e32 v62, 16, v148
	v_and_b32_e32 v63, 0xffff0000, v148
	v_lshlrev_b32_e32 v64, 16, v149
	v_lshlrev_b32_e32 v80, 16, v153
	v_and_b32_e32 v81, 0xffff0000, v153
	v_and_b32_e32 v65, 0xffff0000, v149
	v_add_f32_e32 v50, v98, v50
	v_add_f32_e32 v51, v99, v51
	v_add_f32_e32 v52, v100, v52
	v_add_f32_e32 v53, v101, v53
	v_add_f32_e32 v54, v102, v54
	v_add_f32_e32 v55, v103, v55
	v_add_f32_e32 v56, v104, v56
	v_add_f32_e32 v57, v105, v57
	v_add_f32_e32 v58, v106, v58
	v_add_f32_e32 v59, v107, v59
	v_add_f32_e32 v60, v108, v60
	v_add_f32_e32 v61, v109, v61
	v_add_f32_e32 v62, v110, v62
	v_add_f32_e32 v63, v111, v63
	v_add_f32_e32 v64, v112, v64
	v_add_f32_e32 v80, v96, v80
	v_add_f32_e32 v81, v97, v81
	v_add_f32_e32 v65, v113, v65
	s_branch .LBB0_381

; __device__ __forceinline__ void na_apply(f32x16&p0,f32x16&p1,const u32x4_t*mf,bool ok){
;   if(!ok){ const float NEG=-INFINITY;
;     #pragma unroll
;     for(int rr=0;rr<16;++rr){p0[rr]=NEG;p1[rr]=NEG;}
;     return; }
;   #pragma unroll
;   for(int rr=0;rr<16;++rr){ const unsigned w0=mf[rr>>3][(rr>>1)&3], w1=mf[2+(rr>>3)][(rr>>1)&3];
;     p0[rr]+=__builtin_bit_cast(float,(rr&1)?(w0&0xffff0000u):(w0<<16)); p1[rr]+=__builtin_bit_cast(float,(rr&1)?(w1&0xffff0000u):(w1<<16)); }
; }
.LBB0_408:
	s_andn2_b64 vcc, exec, s[64:65]
	s_cbranch_vccnz .LBB0_410
	s_waitcnt vmcnt(1)
	v_lshlrev_b32_e32 v50, 16, v158
	v_and_b32_e32 v51, 0xffff0000, v158
	v_lshlrev_b32_e32 v52, 16, v159
	v_and_b32_e32 v53, 0xffff0000, v159
	v_lshlrev_b32_e32 v54, 16, v160
	v_and_b32_e32 v55, 0xffff0000, v160
	v_lshlrev_b32_e32 v56, 16, v161
	v_and_b32_e32 v57, 0xffff0000, v161
	v_lshlrev_b32_e32 v58, 16, v150
	v_and_b32_e32 v59, 0xffff0000, v150
	v_lshlrev_b32_e32 v60, 16, v151
	v_and_b32_e32 v61, 0xffff0000, v151
	v_lshlrev_b32_e32 v62, 16, v152
	v_and_b32_e32 v63, 0xffff0000, v152
	v_add_f32_e32 v66, v82, v50
	v_add_f32_e32 v67, v83, v51
	v_lshlrev_b32_e32 v50, 16, v154
	v_and_b32_e32 v51, 0xffff0000, v154
	v_add_f32_e32 v68, v84, v52
	v_add_f32_e32 v69, v85, v53
	v_lshlrev_b32_e32 v52, 16, v155
	v_and_b32_e32 v53, 0xffff0000, v155
	v_add_f32_e32 v70, v86, v54
	v_add_f32_e32 v71, v87, v55
	v_lshlrev_b32_e32 v54, 16, v156
	v_and_b32_e32 v55, 0xffff0000, v156
	v_add_f32_e32 v72, v88, v56
	v_add_f32_e32 v73, v89, v57
	v_lshlrev_b32_e32 v56, 16, v157
	v_and_b32_e32 v57, 0xffff0000, v157
	v_add_f32_e32 v74, v90, v58
	v_add_f32_e32 v75, v91, v59
	v_lshlrev_b32_e32 v58, 16, v146
	v_and_b32_e32 v59, 0xffff0000, v146
	v_add_f32_e32 v76, v92, v60
	v_add_f32_e32 v77, v93, v61
	v_lshlrev_b32_e32 v60, 16, v147
	v_and_b32_e32 v61, 0xffff0000, v147
	v_add_f32_e32 v78, v94, v62
	v_add_f32_e32 v79, v95, v63
	v_lshlrev_b32_e32 v62, 16, v148
	v_and_b32_e32 v63, 0xffff0000, v148
	v_lshlrev_b32_e32 v64, 16, v149
	v_lshlrev_b32_e32 v80, 16, v153
	v_and_b32_e32 v81, 0xffff0000, v153
	v_and_b32_e32 v65, 0xffff0000, v149
	v_add_f32_e32 v50, v98, v50
	v_add_f32_e32 v51, v99, v51
	v_add_f32_e32 v52, v100, v52
	v_add_f32_e32 v53, v101, v53
	v_add_f32_e32 v54, v102, v54
	v_add_f32_e32 v55, v103, v55
	v_add_f32_e32 v56, v104, v56
	v_add_f32_e32 v57, v105, v57
	v_add_f32_e32 v58, v106, v58
	v_add_f32_e32 v59, v107, v59
	v_add_f32_e32 v60, v108, v60
	v_add_f32_e32 v61, v109, v61
	v_add_f32_e32 v62, v110, v62
	v_add_f32_e32 v63, v111, v63
	v_add_f32_e32 v64, v112, v64
	v_add_f32_e32 v80, v96, v80
	v_add_f32_e32 v81, v97, v81
	v_add_f32_e32 v65, v113, v65
	s_branch .LBB0_411
